# attention unit epilogues: row stores widened to dwordx4 via v_permlane32_swap (banded and MLA)
# speedup vs baseline: 1.0868x; 1.0067x over previous
.LBB0_420:
	v_add_f32_e32 v254, v226, v227
	v_add_f32_e32 v255, v228, v229
	v_add_f32_e32 v254, v254, v230
	v_add_f32_e32 v255, v255, v231
	v_add_f32_e32 v254, v254, v232
	v_add_f32_e32 v255, v255, v233
	v_add_f32_e32 v254, v254, v234
	v_add_f32_e32 v255, v255, v235
	v_add_f32_e32 v254, v254, v236
	v_add_f32_e32 v255, v255, v237
	v_add_f32_e32 v254, v254, v238
	v_add_f32_e32 v255, v255, v239
	v_add_f32_e32 v254, v254, v240
	v_add_f32_e32 v255, v255, v241
	v_add_f32_e32 v254, v254, v242
	v_add_f32_e32 v255, v255, v243
	v_add_f32_e32 v254, v254, v244
	v_add_f32_e32 v255, v255, v245
	v_add_f32_e32 v254, v254, v246
	v_add_f32_e32 v255, v255, v247
	v_add_f32_e32 v254, v254, v248
	v_add_f32_e32 v255, v255, v249
	v_add_f32_e32 v254, v254, v166
	v_add_f32_e32 v255, v255, v167
	v_add_f32_e32 v254, v254, v168
	v_add_f32_e32 v255, v255, v169
	v_add_f32_e32 v254, v254, v170
	v_add_f32_e32 v255, v255, v171
	v_add_f32_e32 v254, v254, v172
	v_add_f32_e32 v255, v255, v173
	v_add_f32_e32 v254, v254, v255
	v_add_f32_e32 v143, v143, v254
	v_xor_b32_e32 v0, 32, v187
	v_cmp_lt_i32_e32 vcc, v0, v189
	s_cmp_lg_u64 s[40:41], 0
	s_nop 0
	v_cndmask_b32_e32 v0, v187, v0, vcc
	v_lshlrev_b32_e32 v0, 2, v0
	ds_bpermute_b32 v0, v0, v143
	s_waitcnt lgkmcnt(0)
	v_add_f32_e32 v34, v143, v0
	v_div_scale_f32 v0, s[4:5], v34, v34, 1.0
	v_rcp_f32_e32 v35, v0
	s_nop 0
	v_fma_f32 v36, -v0, v35, 1.0
	v_fmac_f32_e32 v35, v36, v35
	v_div_scale_f32 v36, vcc, 1.0, v34, 1.0
	v_mul_f32_e32 v37, v36, v35
	v_fma_f32 v38, -v0, v37, v36
	v_fmac_f32_e32 v37, v38, v35
	v_fma_f32 v0, -v0, v37, v36
	v_div_fmas_f32 v0, v0, v35, v37
	v_mad_u64_u32 v[36:37], s[4:5], v122, s46, 0
	v_mad_i32_i24 v37, v123, s46, v37
	v_div_fixup_f32 v35, v0, v34, 1.0
	v_lshl_add_u64 v[36:37], v[36:37], 1, s[44:45]
	v_lshlrev_b32_e32 v0, 1, v125
	v_lshl_add_u64 v[36:37], v[36:37], 0, v[0:1]
	s_cselect_b64 s[4:5], -1, 0
	s_and_b64 s[4:5], s[4:5], s[36:37]
	v_lshl_add_u64 v[36:37], v[36:37], 0, v[0:1]
	v_mul_f32_e32 v182, v18, v35
	v_mul_f32_e32 v183, v19, v35
	v_cvt_pk_bf16_f32 v196, v182, v183
	v_mul_f32_e32 v182, v20, v35
	v_mul_f32_e32 v183, v21, v35
	v_cvt_pk_bf16_f32 v197, v182, v183
	v_mul_f32_e32 v182, v22, v35
	v_mul_f32_e32 v183, v23, v35
	v_cvt_pk_bf16_f32 v198, v182, v183
	v_mul_f32_e32 v182, v24, v35
	v_mul_f32_e32 v183, v25, v35
	v_cvt_pk_bf16_f32 v199, v182, v183
	v_mul_f32_e32 v182, v26, v35
	v_mul_f32_e32 v183, v27, v35
	v_cvt_pk_bf16_f32 v200, v182, v183
	v_mul_f32_e32 v182, v28, v35
	v_mul_f32_e32 v183, v29, v35
	v_cvt_pk_bf16_f32 v201, v182, v183
	v_mul_f32_e32 v182, v30, v35
	v_mul_f32_e32 v183, v31, v35
	v_cvt_pk_bf16_f32 v202, v182, v183
	v_mul_f32_e32 v182, v32, v35
	v_mul_f32_e32 v183, v33, v35
	v_cvt_pk_bf16_f32 v203, v182, v183
	v_mul_f32_e32 v182, v2, v35
	v_mul_f32_e32 v183, v3, v35
	v_cvt_pk_bf16_f32 v204, v182, v183
	v_mul_f32_e32 v182, v4, v35
	v_mul_f32_e32 v183, v5, v35
	v_cvt_pk_bf16_f32 v205, v182, v183
	v_mul_f32_e32 v182, v6, v35
	v_mul_f32_e32 v183, v7, v35
	v_cvt_pk_bf16_f32 v206, v182, v183
	v_mul_f32_e32 v182, v8, v35
	v_mul_f32_e32 v183, v9, v35
	v_cvt_pk_bf16_f32 v207, v182, v183
	v_mul_f32_e32 v182, v10, v35
	v_mul_f32_e32 v183, v11, v35
	v_cvt_pk_bf16_f32 v208, v182, v183
	v_mul_f32_e32 v182, v12, v35
	v_mul_f32_e32 v183, v13, v35
	v_cvt_pk_bf16_f32 v209, v182, v183
	v_mul_f32_e32 v182, v14, v35
	v_mul_f32_e32 v183, v15, v35
	v_cvt_pk_bf16_f32 v210, v182, v183
	v_mul_f32_e32 v182, v16, v35
	v_mul_f32_e32 v183, v17, v35
	v_cvt_pk_bf16_f32 v211, v182, v183
	s_nop 1
	v_permlane32_swap_b32_e32 v196, v198
	v_permlane32_swap_b32_e32 v197, v199
	v_permlane32_swap_b32_e32 v200, v202
	v_permlane32_swap_b32_e32 v201, v203
	v_permlane32_swap_b32_e32 v204, v206
	v_permlane32_swap_b32_e32 v205, v207
	v_permlane32_swap_b32_e32 v208, v210
	v_permlane32_swap_b32_e32 v209, v211
	global_store_dwordx4 v[36:37], v[196:199], off
	global_store_dwordx4 v[36:37], v[200:203], off offset:32
	global_store_dwordx4 v[36:37], v[204:207], off offset:64
	global_store_dwordx4 v[36:37], v[208:211], off offset:96
	s_and_saveexec_b64 s[16:17], s[4:5]
	s_cbranch_execz .LBB0_363
	v_log_f32_e32 v0, v34
	v_mad_u64_u32 v[2:3], s[4:5], v122, s42, 0
	v_mad_i32_i24 v3, v123, s42, v3
	v_add_f32_e32 v0, v140, v0
	v_mul_f32_e32 v0, 0x3f317218, v0
	v_lshl_add_u64 v[2:3], v[2:3], 2, s[40:41]
	global_store_dword v[2:3], v0, off
	s_branch .LBB0_363

.LBB0_430:
	v_xor_b32_e32 v0, 32, v187
	v_cmp_lt_i32_e32 vcc, v0, v189
	s_lshl_b32 s1, s1, 7
	v_readlane_b32 s4, v250, 53
	v_cndmask_b32_e32 v0, v187, v0, vcc
	v_lshlrev_b32_e32 v0, 2, v0
	ds_bpermute_b32 v0, v0, v147
	v_readlane_b32 s5, v250, 54
	s_add_u32 s4, s4, s1
	s_addc_u32 s5, s5, 0
	s_add_i32 s0, s0, s28
	s_waitcnt lgkmcnt(0)
	v_add_f32_e32 v0, v147, v0
	v_div_scale_f32 v34, s[16:17], v0, v0, 1.0
	v_rcp_f32_e32 v35, v34
	v_div_scale_f32 v36, vcc, 1.0, v0, 1.0
	s_cmpk_gt_i32 s0, 0x3ff
	v_fma_f32 v37, -v34, v35, 1.0
	v_fmac_f32_e32 v35, v37, v35
	v_mul_f32_e32 v37, v36, v35
	v_fma_f32 v38, -v34, v37, v36
	v_fmac_f32_e32 v37, v38, v35
	v_fma_f32 v34, -v34, v37, v36
	v_div_fmas_f32 v34, v34, v35, v37
	v_div_fixup_f32 v36, v34, v0, 1.0
	v_lshlrev_b64 v[34:35], 10, v[130:131]
	v_lshl_add_u64 v[34:35], s[4:5], 0, v[34:35]
	v_lshlrev_b32_e32 v0, 1, v133
	v_lshl_add_u64 v[34:35], v[34:35], 0, v[0:1]
	v_lshl_add_u64 v[34:35], v[34:35], 0, v[0:1]
	v_mul_f32_e32 v182, v18, v36
	v_mul_f32_e32 v183, v19, v36
	v_cvt_pk_bf16_f32 v204, v182, v183
	v_mul_f32_e32 v182, v20, v36
	v_mul_f32_e32 v183, v21, v36
	v_cvt_pk_bf16_f32 v205, v182, v183
	v_mul_f32_e32 v182, v22, v36
	v_mul_f32_e32 v183, v23, v36
	v_cvt_pk_bf16_f32 v206, v182, v183
	v_mul_f32_e32 v182, v24, v36
	v_mul_f32_e32 v183, v25, v36
	v_cvt_pk_bf16_f32 v207, v182, v183
	v_mul_f32_e32 v182, v26, v36
	v_mul_f32_e32 v183, v27, v36
	v_cvt_pk_bf16_f32 v208, v182, v183
	v_mul_f32_e32 v182, v28, v36
	v_mul_f32_e32 v183, v29, v36
	v_cvt_pk_bf16_f32 v209, v182, v183
	v_mul_f32_e32 v182, v30, v36
	v_mul_f32_e32 v183, v31, v36
	v_cvt_pk_bf16_f32 v210, v182, v183
	v_mul_f32_e32 v182, v32, v36
	v_mul_f32_e32 v183, v33, v36
	v_cvt_pk_bf16_f32 v211, v182, v183
	v_mul_f32_e32 v182, v2, v36
	v_mul_f32_e32 v183, v3, v36
	v_cvt_pk_bf16_f32 v212, v182, v183
	v_mul_f32_e32 v182, v4, v36
	v_mul_f32_e32 v183, v5, v36
	v_cvt_pk_bf16_f32 v213, v182, v183
	v_mul_f32_e32 v182, v6, v36
	v_mul_f32_e32 v183, v7, v36
	v_cvt_pk_bf16_f32 v214, v182, v183
	v_mul_f32_e32 v182, v8, v36
	v_mul_f32_e32 v183, v9, v36
	v_cvt_pk_bf16_f32 v215, v182, v183
	v_mul_f32_e32 v182, v10, v36
	v_mul_f32_e32 v183, v11, v36
	v_cvt_pk_bf16_f32 v216, v182, v183
	v_mul_f32_e32 v182, v12, v36
	v_mul_f32_e32 v183, v13, v36
	v_cvt_pk_bf16_f32 v217, v182, v183
	v_mul_f32_e32 v182, v14, v36
	v_mul_f32_e32 v183, v15, v36
	v_cvt_pk_bf16_f32 v218, v182, v183
	v_mul_f32_e32 v182, v16, v36
	v_mul_f32_e32 v183, v17, v36
	v_cvt_pk_bf16_f32 v219, v182, v183
	s_nop 1
	v_permlane32_swap_b32_e32 v204, v206
	v_permlane32_swap_b32_e32 v205, v207
	v_permlane32_swap_b32_e32 v208, v210
	v_permlane32_swap_b32_e32 v209, v211
	v_permlane32_swap_b32_e32 v212, v214
	v_permlane32_swap_b32_e32 v213, v215
	v_permlane32_swap_b32_e32 v216, v218
	v_permlane32_swap_b32_e32 v217, v219
	global_store_dwordx4 v[34:35], v[204:207], off
	global_store_dwordx4 v[34:35], v[208:211], off offset:32
	global_store_dwordx4 v[34:35], v[212:215], off offset:64
	global_store_dwordx4 v[34:35], v[216:219], off offset:96
	s_cbranch_scc1 .LBB0_351
